# strategy 7.4 extended: waves 0-3 also run the prep units at user priority 1 (wave 0's serial triangular solve shares its SIMD with wave 4)
# speedup vs baseline: 1.0070x; 1.0015x over previous
; __device__ __forceinline__ int my_tid() { int t = (int)threadIdx.x; asm volatile("" : "+v"(t)); return t; }
; __device__ void prep_unit(unsigned char* lds, int bh, int n, const bf16_t* pc, const float* scal, const float* convw  , float alog, float dtb, unsigned char* unit, float* egl, unsigned* flag, unsigned fval) {
;     const int tid = my_tid(), wid = tid >> 6, lane = tid & 63, b = bh >> 2, h = bh & 3;
;     float* qT = (float*)lds; float* kT = (float*)(lds + 34816); float* vT = (float*)(lds + 69632);
;     float* Am = (float*)(lds + 104448); float* At = (float*)(lds + 121856);
;     float* gc = (float*)(lds + 139264); float* bet = gc + 64; float* rq = gc + 128; float* rk = gc + 192;
;     bf16_t* stage = (bf16_t*)(lds + 140288); float* ssp = (float*)(lds + 140288);
;     const size_t row0 = (size_t)b * SEQ + (size_t)n * 64;
;     const __amdgpu_buffer_rsrc_t ur = __builtin_amdgcn_make_buffer_rsrc(unit, 0, PREP_UNIT, 0x00020000);
;     ...
;     for (int rep1 = 0; rep1 < REP_S1; ++rep1) {
;     if (tid < 384) {
;         const int part = tid >> 7, cg8 = (tid & 127) >> 3, run = tid & 7, col = part * 512 + h * 128 + cg8 * 8;
; __device__ void run_phase(const Params& p, unsigned char* lds, int ph) {
;     ...
;             else if (it < 2096) { const int j = it - 48, n = j >> 4, bh = j & 15, h = bh & 3;
;                 prep_unit(lds, bh, n, (const bf16_t*)(ws + WS_PC), (const float*)(ws + WS_SCAL), p.in[I_CONVW] + (size_t)l * 4 * 1536, p.in[I_ALOG][l * 4 + h], p.in[I_DTB][l * 4 + h],
;                           ws + WS_PREP + (size_t)(bh * 128 + n) * PREP_UNIT, (float*)(ws + WS_EGL), uflag + bh * 128 + n, fval); }
.LBB0_302:
	s_or_saveexec_b64 s[12:13], s[0:1]
	v_readlane_b32 s4, v255, 45
	v_readlane_b32 s5, v255, 46
	s_xor_b64 exec, exec, s[12:13]
	s_cbranch_execz .LBB0_449
	s_branch .Lpr_p
.Lpr_pback:
	v_or_b32_e32 v4, s48, v2
	v_ashrrev_i32_e32 v5, 31, v4
	v_readlane_b32 s0, v254, 61
	v_lshlrev_b64 v[4:5], 2, v[4:5]
	v_readlane_b32 s1, v254, 62
	v_subrev_u32_e32 v0, 48, v90
	v_lshrrev_b32_e32 v0, 4, v0
	v_lshl_add_u64 v[6:7], s[0:1], 0, v[4:5]
	v_readlane_b32 s0, v254, 63
	v_readlane_b32 s1, v255, 0
	global_load_dword v252, v[6:7], off
	v_mov_b32_e32 v156, v212
	v_lshl_add_u64 v[4:5], s[0:1], 0, v[4:5]
	global_load_dword v253, v[4:5], off
	v_lshlrev_b32_e32 v5, 11, v90
	s_movk_i32 s0, 0x17f
	v_and_b32_e32 v6, 0x6000, v5
	v_and_b32_e32 v157, 63, v156
	v_mov_b32_e32 v7, v1
	v_lshlrev_b64 v[8:9], 6, v[0:1]
	v_cmp_lt_i32_e32 vcc, s0, v156
	s_movk_i32 s0, 0x7f
	v_lshl_add_u64 v[22:23], v[8:9], 0, v[6:7]
	v_cmp_gt_u32_e64 s[10:11], s46, v156
	v_cmp_lt_u32_e64 s[8:9], s0, v156
	v_cmp_gt_u32_e64 s[6:7], 8, v157
	s_and_saveexec_b64 s[0:1], vcc
	s_xor_b64 s[0:1], exec, s[0:1]
	s_cbranch_execz .LBB0_307
	s_movk_i32 s2, 0x1c0
	v_cmp_gt_u32_e32 vcc, s2, v156
	s_and_saveexec_b64 s[2:3], vcc
	s_cbranch_execz .LBB0_306
	v_add_u32_e32 v6, 0xfffffe80, v156
	v_mov_b32_e32 v7, v1
	v_lshl_add_u64 v[8:9], v[22:23], 0, v[6:7]
	v_readlane_b32 s4, v255, 37
	v_lshlrev_b64 v[8:9], 6, v[8:9]
	v_readlane_b32 s5, v255, 38
	v_lshlrev_b32_e32 v10, 2, v2
	v_mov_b32_e32 v11, v1
	v_lshl_add_u64 v[8:9], s[4:5], 0, v[8:9]
	v_lshl_add_u64 v[8:9], v[8:9], 0, v[10:11]
	v_lshl_add_u32 v5, v6, 2, 0
	v_add_u32_e32 v6, 0x22100, v5
	s_branch .Lps1_a

; __device__ void run_phase(const Params& p, unsigned char* lds, int ph) {
;     ...
;             else if (it < 2096) { const int j = it - 48, n = j >> 4, bh = j & 15, h = bh & 3;
;                 prep_unit(lds, bh, n, (const bf16_t*)(ws + WS_PC), (const float*)(ws + WS_SCAL), p.in[I_CONVW] + (size_t)l * 4 * 1536, p.in[I_ALOG][l * 4 + h], p.in[I_DTB][l * 4 + h],
;                           ws + WS_PREP + (size_t)(bh * 128 + n) * PREP_UNIT, (float*)(ws + WS_EGL), uflag + bh * 128 + n, fval); }
;             else if (it < 2608) { const int j = it - 2096, qb = j & 31, bh = j >> 5, b = bh >> 2, h = bh & 3;
.Lpr_a1:
	v_add_u32_e32 v86, 0xfffff7d0, v90
	s_branch .Lpr_aback
.Lpr_p:
	v_readfirstlane_b32 s98, v212
	s_nop 3
	s_cmp_lt_u32 s98, 0x100
	s_cbranch_scc0 .Lpr_p1
	s_setprio 1
.Lpr_p1:
	v_and_b32_e32 v2, 3, v90
	s_branch .Lpr_pback
